# resid epilogue output stage: boundary-straddling tiles keep both conditioning parameter sets in registers and select per lane instead of reloading per row block
# speedup vs baseline: 1.0074x; 1.0043x over previous
.LBB0_946:
	s_or_b64 exec, exec, s[2:3]
	s_lshl_b32 s2, s17, 10
	s_mov_b32 s3, s69
	s_lshl_b64 s[2:3], s[2:3], 2
	s_add_u32 s2, s80, s2
	s_addc_u32 s3, s81, s3
	v_lshl_add_u64 v[2:3], v[242:243], 2, s[2:3]
	s_mov_b64 s[2:3], 0x55ac100
	v_lshl_add_u64 v[106:107], v[2:3], 0, s[2:3]
	s_mov_b32 s2, 0x55ac000
	v_add_co_u32_e32 v4, vcc, s2, v2
	s_mov_b64 s[2:3], 0x55b4100
	s_nop 0
	v_addc_co_u32_e32 v5, vcc, 0, v3, vcc
	v_lshl_add_u64 v[108:109], v[2:3], 0, s[2:3]
	v_add_co_u32_e32 v2, vcc, 0x55b4000, v2
	s_waitcnt lgkmcnt(0)
	s_barrier
	s_nop 0
	v_addc_co_u32_e32 v3, vcc, 0, v3, vcc
	flat_load_dwordx4 v[12:15], v[4:5] offset:256
	flat_load_dwordx4 v[16:19], v[2:3] offset:256
	s_nop 0
	flat_load_dwordx4 v[4:7], v[106:107] offset:16
	flat_load_dwordx4 v[8:11], v[108:109] offset:16
	s_cmp_lg_u64 s[8:9], 0
	s_cselect_b64 s[2:3], -1, 0
	s_cmp_eq_u64 s[8:9], 0
	s_cbranch_scc1 .LBB0_948
	s_lshl_b64 s[4:5], s[68:69], 2
	s_add_u32 s4, s8, s4
	s_addc_u32 s5, s9, s5
	v_lshl_add_u64 v[2:3], v[242:243], 2, s[4:5]
	v_add_co_u32_e32 v24, vcc, 0x1000, v2
	s_nop 1
	v_addc_co_u32_e32 v25, vcc, 0, v3, vcc
	flat_load_dwordx4 v[20:23], v[24:25]
	s_nop 0
	flat_load_dwordx4 v[24:27], v[24:25] offset:16
	s_nop 0
	flat_load_dwordx4 v[32:35], v[2:3]
	flat_load_dwordx4 v[36:39], v[2:3] offset:16
	s_and_b64 vcc, exec, s[0:1]
	s_cbranch_vccnz .Lap_h0_a
	v_add_co_u32_e32 v132, vcc, 0x6000, v2
	s_nop 1
	v_addc_co_u32_e32 v133, vcc, 0, v3, vcc
	v_add_co_u32_e32 v134, vcc, 0x7000, v2
	s_nop 1
	v_addc_co_u32_e32 v135, vcc, 0, v3, vcc
	flat_load_dwordx4 v[166:169], v[134:135]
	flat_load_dwordx4 v[170:173], v[134:135] offset:16
	flat_load_dwordx4 v[178:181], v[132:133]
	flat_load_dwordx4 v[182:185], v[132:133] offset:16
.Lap_h0_a:
	s_waitcnt vmcnt(0) lgkmcnt(0)
	v_pk_add_f32 v[42:43], v[22:23], 1.0 op_sel_hi:[1,0]
	v_pk_add_f32 v[40:41], v[20:21], 1.0 op_sel_hi:[1,0]
	v_pk_add_f32 v[50:51], v[26:27], 1.0 op_sel_hi:[1,0]
	v_pk_add_f32 v[48:49], v[24:25], 1.0 op_sel_hi:[1,0]
	s_and_b64 vcc, exec, s[0:1]
	s_cbranch_vccnz .Lap_h0_b
	v_mov_b64_e32 v[142:143], v[40:41]
	v_mov_b64_e32 v[144:145], v[42:43]
	v_mov_b64_e32 v[146:147], v[48:49]
	v_mov_b64_e32 v[148:149], v[50:51]
	v_mov_b64_e32 v[154:155], v[32:33]
	v_mov_b64_e32 v[156:157], v[34:35]
	v_mov_b64_e32 v[158:159], v[36:37]
	v_mov_b64_e32 v[160:161], v[38:39]
	v_pk_add_f32 v[166:167], v[166:167], 1.0 op_sel_hi:[1,0]
	v_pk_add_f32 v[168:169], v[168:169], 1.0 op_sel_hi:[1,0]
	v_pk_add_f32 v[170:171], v[170:171], 1.0 op_sel_hi:[1,0]
	v_pk_add_f32 v[172:173], v[172:173], 1.0 op_sel_hi:[1,0]
.Lap_h0_b:
	s_branch .LBB0_949
.LBB0_948:
	v_mov_b32_e32 v2, v1
	v_mov_b32_e32 v3, v1
	v_mov_b32_e32 v0, v1
	v_mov_b64_e32 v[34:35], v[2:3]
	v_mov_b64_e32 v[38:39], v[2:3]
	v_mov_b64_e32 v[42:43], v[2:3]
	v_mov_b64_e32 v[50:51], v[2:3]
	v_mov_b64_e32 v[32:33], v[0:1]
	v_mov_b64_e32 v[36:37], v[0:1]
	v_mov_b64_e32 v[40:41], v[0:1]
	v_mov_b64_e32 v[48:49], v[0:1]
.LBB0_949:
	v_readlane_b32 s4, v254, 12
	v_lshlrev_b32_e32 v111, 10, v249
	v_add_u32_e32 v0, v111, v242
	v_lshl_add_u32 v110, v253, 3, s4
	ds_read_b64 v[2:3], v110 offset:8192
	s_and_b64 vcc, exec, s[2:3]
	s_waitcnt lgkmcnt(0)
	v_sub_f32_e32 v21, v215, v2
	v_sub_f32_e32 v20, v214, v2
	v_sub_f32_e32 v23, v217, v2
	v_sub_f32_e32 v22, v216, v2
	v_pk_mul_f32 v[22:23], v[2:3], v[22:23] op_sel:[1,0]
	v_pk_mul_f32 v[20:21], v[2:3], v[20:21] op_sel:[1,0]
	s_waitcnt vmcnt(0)
	v_pk_fma_f32 v[52:53], v[12:13], v[22:23], v[16:17]
	v_pk_fma_f32 v[54:55], v[14:15], v[20:21], v[18:19]
	v_sub_f32_e32 v21, v211, v2
	v_sub_f32_e32 v20, v210, v2
	v_sub_f32_e32 v23, v213, v2
	v_sub_f32_e32 v22, v212, v2
	v_pk_mul_f32 v[22:23], v[2:3], v[22:23] op_sel:[1,0]
	v_pk_mul_f32 v[2:3], v[2:3], v[20:21] op_sel:[1,0]
	v_pk_fma_f32 v[56:57], v[4:5], v[22:23], v[8:9]
	v_pk_fma_f32 v[58:59], v[6:7], v[2:3], v[10:11]
	s_cbranch_vccz .LBB0_981
	v_mov_b64_e32 v[20:21], v[32:33]
	v_mov_b64_e32 v[24:25], v[36:37]
	v_mov_b64_e32 v[28:29], v[40:41]
	v_mov_b64_e32 v[44:45], v[48:49]
	s_and_b64 vcc, exec, s[0:1]
	v_mov_b64_e32 v[22:23], v[34:35]
	v_mov_b64_e32 v[26:27], v[38:39]
	v_mov_b64_e32 v[30:31], v[42:43]
	v_mov_b64_e32 v[46:47], v[50:51]
	s_cbranch_vccnz .LBB0_952
	v_add_u32_e32 v2, 0xffffe000, v249
	v_lshrrev_b32_e32 v2, 10, v2
	s_movk_i32 s4, 0x1800
	v_mad_u32_u24 v2, v2, s4, s4
	s_movk_i32 s4, 0x1fff
	v_cmp_lt_i32_e32 vcc, s4, v249
	v_mov_b32_e32 v3, v1
	s_nop 0
	v_cndmask_b32_e32 v2, 0, v2, vcc
	v_cmp_ne_u32_e32 vcc, s68, v2
	v_cndmask_b32_e32 v30, v144, v168, vcc
	v_cndmask_b32_e32 v31, v145, v169, vcc
	v_cndmask_b32_e32 v28, v142, v166, vcc
	v_cndmask_b32_e32 v29, v143, v167, vcc
	v_cndmask_b32_e32 v46, v148, v172, vcc
	v_cndmask_b32_e32 v47, v149, v173, vcc
	v_cndmask_b32_e32 v44, v146, v170, vcc
	v_cndmask_b32_e32 v45, v147, v171, vcc
	v_cndmask_b32_e32 v20, v154, v178, vcc
	v_cndmask_b32_e32 v21, v155, v179, vcc
	v_cndmask_b32_e32 v22, v156, v180, vcc
	v_cndmask_b32_e32 v23, v157, v181, vcc
	v_cndmask_b32_e32 v24, v158, v182, vcc
	v_cndmask_b32_e32 v25, v159, v183, vcc
	v_cndmask_b32_e32 v26, v160, v184, vcc
	v_cndmask_b32_e32 v27, v161, v185, vcc

.LBB0_954:
	ds_read_b64 v[2:3], v110 offset:8320
	v_add_u32_e32 v112, 0x4000, v111
	v_cndmask_b32_e64 v0, 0, 1, s[2:3]
	v_cmp_ne_u32_e64 s[4:5], 1, v0
	s_andn2_b64 vcc, exec, s[2:3]
	s_waitcnt lgkmcnt(0)
	v_sub_f32_e32 v33, v193, v2
	v_sub_f32_e32 v32, v192, v2
	v_sub_f32_e32 v35, v195, v2
	v_sub_f32_e32 v34, v194, v2
	v_pk_mul_f32 v[34:35], v[2:3], v[34:35] op_sel:[1,0]
	v_pk_mul_f32 v[32:33], v[2:3], v[32:33] op_sel:[1,0]
	v_pk_fma_f32 v[52:53], v[12:13], v[34:35], v[16:17]
	v_pk_fma_f32 v[54:55], v[14:15], v[32:33], v[18:19]
	v_sub_f32_e32 v33, v187, v2
	v_sub_f32_e32 v32, v186, v2
	v_sub_f32_e32 v35, v189, v2
	v_sub_f32_e32 v34, v188, v2
	v_pk_mul_f32 v[34:35], v[2:3], v[34:35] op_sel:[1,0]
	v_pk_mul_f32 v[2:3], v[2:3], v[32:33] op_sel:[1,0]
	v_pk_fma_f32 v[56:57], v[4:5], v[34:35], v[8:9]
	v_pk_fma_f32 v[58:59], v[6:7], v[2:3], v[10:11]
	v_add_u32_e32 v0, v112, v242
	s_cbranch_vccnz .LBB0_982
	v_mov_b64_e32 v[34:35], v[22:23]
	v_mov_b64_e32 v[38:39], v[26:27]
	v_mov_b64_e32 v[42:43], v[30:31]
	v_mov_b64_e32 v[50:51], v[46:47]
	s_and_b64 vcc, exec, s[0:1]
	v_mov_b64_e32 v[32:33], v[20:21]
	v_mov_b64_e32 v[36:37], v[24:25]
	v_mov_b64_e32 v[40:41], v[28:29]
	v_mov_b64_e32 v[48:49], v[44:45]
	s_cbranch_vccnz .LBB0_957
	v_add_u32_e32 v2, 0xffffe010, v249
	v_lshrrev_b32_e32 v2, 10, v2
	s_movk_i32 s2, 0x1800
	v_mad_u32_u24 v2, v2, s2, s2
	s_movk_i32 s2, 0x1fef
	v_cmp_lt_i32_e32 vcc, s2, v249
	v_mov_b32_e32 v3, v1
	s_nop 0
	v_cndmask_b32_e32 v2, 0, v2, vcc
	v_cmp_ne_u32_e32 vcc, s68, v2
	v_cndmask_b32_e32 v42, v144, v168, vcc
	v_cndmask_b32_e32 v43, v145, v169, vcc
	v_cndmask_b32_e32 v40, v142, v166, vcc
	v_cndmask_b32_e32 v41, v143, v167, vcc
	v_cndmask_b32_e32 v50, v148, v172, vcc
	v_cndmask_b32_e32 v51, v149, v173, vcc
	v_cndmask_b32_e32 v48, v146, v170, vcc
	v_cndmask_b32_e32 v49, v147, v171, vcc
	v_cndmask_b32_e32 v32, v154, v178, vcc
	v_cndmask_b32_e32 v33, v155, v179, vcc
	v_cndmask_b32_e32 v34, v156, v180, vcc
	v_cndmask_b32_e32 v35, v157, v181, vcc
	v_cndmask_b32_e32 v36, v158, v182, vcc
	v_cndmask_b32_e32 v37, v159, v183, vcc
	v_cndmask_b32_e32 v38, v160, v184, vcc
	v_cndmask_b32_e32 v39, v161, v185, vcc

.LBB0_959:
	ds_read_b64 v[2:3], v110 offset:8448
	v_add_u32_e32 v113, 0x8000, v111
	s_and_b64 vcc, exec, s[4:5]
	v_add_u32_e32 v0, v113, v242
	s_waitcnt lgkmcnt(0)
	v_sub_f32_e32 v21, v175, v2
	v_sub_f32_e32 v20, v174, v2
	v_sub_f32_e32 v23, v177, v2
	v_sub_f32_e32 v22, v176, v2
	v_pk_mul_f32 v[22:23], v[2:3], v[22:23] op_sel:[1,0]
	v_pk_mul_f32 v[20:21], v[2:3], v[20:21] op_sel:[1,0]
	v_pk_fma_f32 v[24:25], v[12:13], v[22:23], v[16:17]
	v_pk_fma_f32 v[26:27], v[14:15], v[20:21], v[18:19]
	v_sub_f32_e32 v21, v163, v2
	v_sub_f32_e32 v20, v162, v2
	v_sub_f32_e32 v23, v165, v2
	v_sub_f32_e32 v22, v164, v2
	v_pk_mul_f32 v[22:23], v[2:3], v[22:23] op_sel:[1,0]
	v_pk_mul_f32 v[2:3], v[2:3], v[20:21] op_sel:[1,0]
	v_pk_fma_f32 v[56:57], v[4:5], v[22:23], v[8:9]
	v_pk_fma_f32 v[58:59], v[6:7], v[2:3], v[10:11]
	s_cbranch_vccnz .LBB0_983
	v_mov_b64_e32 v[20:21], v[32:33]
	v_mov_b64_e32 v[28:29], v[36:37]
	v_mov_b64_e32 v[46:47], v[42:43]
	v_mov_b64_e32 v[54:55], v[50:51]
	s_and_b64 vcc, exec, s[0:1]
	v_mov_b64_e32 v[22:23], v[34:35]
	v_mov_b64_e32 v[30:31], v[38:39]
	v_mov_b64_e32 v[44:45], v[40:41]
	v_mov_b64_e32 v[52:53], v[48:49]
	s_cbranch_vccnz .LBB0_962
	v_add_u32_e32 v2, 0xffffe020, v249
	v_lshrrev_b32_e32 v2, 10, v2
	s_movk_i32 s2, 0x1800
	v_mad_u32_u24 v2, v2, s2, s2
	s_movk_i32 s2, 0x1fdf
	v_cmp_lt_i32_e32 vcc, s2, v249
	v_mov_b32_e32 v3, v1
	s_nop 0
	v_cndmask_b32_e32 v2, 0, v2, vcc
	v_cmp_ne_u32_e32 vcc, s68, v2
	v_cndmask_b32_e32 v46, v144, v168, vcc
	v_cndmask_b32_e32 v47, v145, v169, vcc
	v_cndmask_b32_e32 v44, v142, v166, vcc
	v_cndmask_b32_e32 v45, v143, v167, vcc
	v_cndmask_b32_e32 v54, v148, v172, vcc
	v_cndmask_b32_e32 v55, v149, v173, vcc
	v_cndmask_b32_e32 v52, v146, v170, vcc
	v_cndmask_b32_e32 v53, v147, v171, vcc
	v_cndmask_b32_e32 v20, v154, v178, vcc
	v_cndmask_b32_e32 v21, v155, v179, vcc
	v_cndmask_b32_e32 v22, v156, v180, vcc
	v_cndmask_b32_e32 v23, v157, v181, vcc
	v_cndmask_b32_e32 v28, v158, v182, vcc
	v_cndmask_b32_e32 v29, v159, v183, vcc
	v_cndmask_b32_e32 v30, v160, v184, vcc
	v_cndmask_b32_e32 v31, v161, v185, vcc

.LBB0_964:
	ds_read_b64 v[2:3], v110 offset:8960
	v_add_u32_e32 v118, 0x18000, v111
	s_and_b64 vcc, exec, s[4:5]
	v_add_u32_e32 v0, v118, v242
	s_waitcnt lgkmcnt(0)
	v_sub_f32_e32 v25, v151, v2
	v_sub_f32_e32 v24, v150, v2
	v_sub_f32_e32 v27, v153, v2
	v_sub_f32_e32 v26, v152, v2
	v_pk_mul_f32 v[26:27], v[2:3], v[26:27] op_sel:[1,0]
	v_pk_mul_f32 v[24:25], v[2:3], v[24:25] op_sel:[1,0]
	v_pk_fma_f32 v[48:49], v[12:13], v[26:27], v[16:17]
	v_pk_fma_f32 v[50:51], v[14:15], v[24:25], v[18:19]
	v_sub_f32_e32 v25, v139, v2
	v_sub_f32_e32 v24, v138, v2
	v_sub_f32_e32 v27, v141, v2
	v_sub_f32_e32 v26, v140, v2
	v_pk_mul_f32 v[26:27], v[2:3], v[26:27] op_sel:[1,0]
	v_pk_mul_f32 v[2:3], v[2:3], v[24:25] op_sel:[1,0]
	v_pk_fma_f32 v[56:57], v[4:5], v[26:27], v[8:9]
	v_pk_fma_f32 v[58:59], v[6:7], v[2:3], v[10:11]
	s_cbranch_vccnz .LBB0_984
	v_mov_b64_e32 v[26:27], v[22:23]
	v_mov_b64_e32 v[34:35], v[30:31]
	v_mov_b64_e32 v[36:37], v[44:45]
	v_mov_b64_e32 v[40:41], v[52:53]
	s_and_b64 vcc, exec, s[0:1]
	v_mov_b64_e32 v[24:25], v[20:21]
	v_mov_b64_e32 v[32:33], v[28:29]
	v_mov_b64_e32 v[38:39], v[46:47]
	v_mov_b64_e32 v[42:43], v[54:55]
	s_cbranch_vccnz .LBB0_967
	v_add_u32_e32 v2, 0xffffe060, v249
	v_lshrrev_b32_e32 v2, 10, v2
	s_movk_i32 s2, 0x1800
	v_mad_u32_u24 v2, v2, s2, s2
	s_movk_i32 s2, 0x1f9f
	v_cmp_lt_i32_e32 vcc, s2, v249
	v_mov_b32_e32 v3, v1
	s_nop 0
	v_cndmask_b32_e32 v2, 0, v2, vcc
	v_cmp_ne_u32_e32 vcc, s68, v2
	v_cndmask_b32_e32 v38, v144, v168, vcc
	v_cndmask_b32_e32 v39, v145, v169, vcc
	v_cndmask_b32_e32 v36, v142, v166, vcc
	v_cndmask_b32_e32 v37, v143, v167, vcc
	v_cndmask_b32_e32 v42, v148, v172, vcc
	v_cndmask_b32_e32 v43, v149, v173, vcc
	v_cndmask_b32_e32 v40, v146, v170, vcc
	v_cndmask_b32_e32 v41, v147, v171, vcc
	v_cndmask_b32_e32 v24, v154, v178, vcc
	v_cndmask_b32_e32 v25, v155, v179, vcc
	v_cndmask_b32_e32 v26, v156, v180, vcc
	v_cndmask_b32_e32 v27, v157, v181, vcc
	v_cndmask_b32_e32 v32, v158, v182, vcc
	v_cndmask_b32_e32 v33, v159, v183, vcc
	v_cndmask_b32_e32 v34, v160, v184, vcc
	v_cndmask_b32_e32 v35, v161, v185, vcc

.LBB0_969:
	ds_read_b64 v[2:3], v110 offset:9088
	s_and_b64 vcc, exec, s[4:5]
	s_waitcnt lgkmcnt(0)
	v_sub_f32_e32 v21, v127, v2
	v_sub_f32_e32 v20, v126, v2
	v_sub_f32_e32 v23, v129, v2
	v_sub_f32_e32 v22, v128, v2
	v_pk_mul_f32 v[22:23], v[2:3], v[22:23] op_sel:[1,0]
	v_pk_mul_f32 v[20:21], v[2:3], v[20:21] op_sel:[1,0]
	v_pk_fma_f32 v[52:53], v[12:13], v[22:23], v[16:17]
	v_pk_fma_f32 v[54:55], v[14:15], v[20:21], v[18:19]
	v_sub_f32_e32 v21, v115, v2
	v_sub_f32_e32 v20, v114, v2
	v_sub_f32_e32 v23, v117, v2
	v_sub_f32_e32 v22, v116, v2
	v_pk_mul_f32 v[22:23], v[2:3], v[22:23] op_sel:[1,0]
	v_pk_mul_f32 v[2:3], v[2:3], v[20:21] op_sel:[1,0]
	v_add_u32_e32 v114, 0x1c000, v111
	v_pk_fma_f32 v[58:59], v[6:7], v[2:3], v[10:11]
	v_pk_fma_f32 v[56:57], v[4:5], v[22:23], v[8:9]
	v_add_u32_e32 v0, v114, v242
	s_cbranch_vccnz .LBB0_985
	v_mov_b64_e32 v[30:31], v[26:27]
	v_mov_b64_e32 v[20:21], v[32:33]
	v_mov_b64_e32 v[46:47], v[38:39]
	v_mov_b64_e32 v[50:51], v[42:43]
	s_and_b64 vcc, exec, s[0:1]
	v_mov_b64_e32 v[28:29], v[24:25]
	v_mov_b64_e32 v[22:23], v[34:35]
	v_mov_b64_e32 v[44:45], v[36:37]
	v_mov_b64_e32 v[48:49], v[40:41]
	s_cbranch_vccnz .LBB0_972
	v_add_u32_e32 v2, 0xffffe070, v249
	v_lshrrev_b32_e32 v2, 10, v2
	s_movk_i32 s2, 0x1800
	v_mad_u32_u24 v2, v2, s2, s2
	s_movk_i32 s2, 0x1f8f
	v_cmp_lt_i32_e32 vcc, s2, v249
	v_mov_b32_e32 v3, v1
	s_nop 0
	v_cndmask_b32_e32 v2, 0, v2, vcc
	v_cmp_ne_u32_e32 vcc, s68, v2
	v_cndmask_b32_e32 v46, v144, v168, vcc
	v_cndmask_b32_e32 v47, v145, v169, vcc
	v_cndmask_b32_e32 v44, v142, v166, vcc
	v_cndmask_b32_e32 v45, v143, v167, vcc
	v_cndmask_b32_e32 v50, v148, v172, vcc
	v_cndmask_b32_e32 v51, v149, v173, vcc
	v_cndmask_b32_e32 v48, v146, v170, vcc
	v_cndmask_b32_e32 v49, v147, v171, vcc
	v_cndmask_b32_e32 v28, v154, v178, vcc
	v_cndmask_b32_e32 v29, v155, v179, vcc
	v_cndmask_b32_e32 v30, v156, v180, vcc
	v_cndmask_b32_e32 v31, v157, v181, vcc
	v_cndmask_b32_e32 v20, v158, v182, vcc
	v_cndmask_b32_e32 v21, v159, v183, vcc
	v_cndmask_b32_e32 v22, v160, v184, vcc
	v_cndmask_b32_e32 v23, v161, v185, vcc

.LBB0_974:
	ds_read_b64 v[2:3], v110 offset:9216
	s_and_b64 vcc, exec, s[4:5]
	s_waitcnt lgkmcnt(0)
	v_sub_f32_e32 v25, v103, v2
	v_sub_f32_e32 v24, v102, v2
	v_sub_f32_e32 v27, v105, v2
	v_sub_f32_e32 v26, v104, v2
	v_pk_mul_f32 v[26:27], v[2:3], v[26:27] op_sel:[1,0]
	v_pk_mul_f32 v[24:25], v[2:3], v[24:25] op_sel:[1,0]
	v_pk_fma_f32 v[12:13], v[12:13], v[26:27], v[16:17]
	v_pk_fma_f32 v[14:15], v[14:15], v[24:25], v[18:19]
	v_sub_f32_e32 v17, v99, v2
	v_sub_f32_e32 v16, v98, v2
	v_sub_f32_e32 v19, v101, v2
	v_sub_f32_e32 v18, v100, v2
	v_pk_mul_f32 v[18:19], v[2:3], v[18:19] op_sel:[1,0]
	v_pk_mul_f32 v[2:3], v[2:3], v[16:17] op_sel:[1,0]
	v_add_u32_e32 v98, 0x20000, v111
	v_pk_fma_f32 v[6:7], v[6:7], v[2:3], v[10:11]
	v_pk_fma_f32 v[4:5], v[4:5], v[18:19], v[8:9]
	v_add_u32_e32 v0, v98, v242
	s_cbranch_vccnz .LBB0_986
	s_and_b64 vcc, exec, s[0:1]
	v_or_b32_e32 v99, 0x80, v242
	s_cbranch_vccnz .LBB0_977
	v_add_u32_e32 v2, 0xffffe080, v249
	v_lshrrev_b32_e32 v2, 10, v2
	s_movk_i32 s2, 0x1800
	v_mad_u32_u24 v2, v2, s2, s2
	s_movk_i32 s2, 0x1f7f
	v_cmp_lt_i32_e32 vcc, s2, v249
	v_mov_b32_e32 v3, v1
	s_nop 0
	v_cndmask_b32_e32 v2, 0, v2, vcc
	v_cmp_ne_u32_e32 vcc, s68, v2
	v_cndmask_b32_e32 v46, v144, v168, vcc
	v_cndmask_b32_e32 v47, v145, v169, vcc
	v_cndmask_b32_e32 v44, v142, v166, vcc
	v_cndmask_b32_e32 v45, v143, v167, vcc
	v_cndmask_b32_e32 v50, v148, v172, vcc
	v_cndmask_b32_e32 v51, v149, v173, vcc
	v_cndmask_b32_e32 v48, v146, v170, vcc
	v_cndmask_b32_e32 v49, v147, v171, vcc
	v_cndmask_b32_e32 v28, v154, v178, vcc
	v_cndmask_b32_e32 v29, v155, v179, vcc
	v_cndmask_b32_e32 v30, v156, v180, vcc
	v_cndmask_b32_e32 v31, v157, v181, vcc
	v_cndmask_b32_e32 v20, v158, v182, vcc
	v_cndmask_b32_e32 v21, v159, v183, vcc
	v_cndmask_b32_e32 v22, v160, v184, vcc
	v_cndmask_b32_e32 v23, v161, v185, vcc

.LBB0_979:
	flat_load_dwordx4 v[12:15], v[106:107] offset:512
	flat_load_dwordx4 v[4:7], v[106:107] offset:528
	flat_load_dwordx4 v[16:19], v[108:109] offset:512
	flat_load_dwordx4 v[8:11], v[108:109] offset:528
	s_and_b64 vcc, exec, s[4:5]
	s_cbranch_vccnz .LBB0_987
	s_lshl_b64 s[2:3], s[68:69], 2
	s_add_u32 s2, s8, s2
	s_addc_u32 s3, s9, s3
	v_lshl_add_u64 v[2:3], v[242:243], 2, s[2:3]
	v_add_co_u32_e32 v24, vcc, 0x1000, v2
	s_nop 1
	v_addc_co_u32_e32 v25, vcc, 0, v3, vcc
	flat_load_dwordx4 v[20:23], v[24:25] offset:512
	flat_load_dwordx4 v[28:31], v[24:25] offset:528
	s_nop 0
	flat_load_dwordx4 v[24:27], v[2:3] offset:512
	flat_load_dwordx4 v[32:35], v[2:3] offset:528
	s_and_b64 vcc, exec, s[0:1]
	s_cbranch_vccnz .Lap_h1_a
	v_add_co_u32_e32 v132, vcc, 0x6000, v2
	s_nop 1
	v_addc_co_u32_e32 v133, vcc, 0, v3, vcc
	v_add_co_u32_e32 v134, vcc, 0x7000, v2
	s_nop 1
	v_addc_co_u32_e32 v135, vcc, 0, v3, vcc
	flat_load_dwordx4 v[166:169], v[134:135] offset:512
	flat_load_dwordx4 v[170:173], v[134:135] offset:528
	flat_load_dwordx4 v[178:181], v[132:133] offset:512
	flat_load_dwordx4 v[182:185], v[132:133] offset:528
.Lap_h1_a:
	s_waitcnt vmcnt(0) lgkmcnt(0)
	v_pk_add_f32 v[42:43], v[22:23], 1.0 op_sel_hi:[1,0]
	v_pk_add_f32 v[40:41], v[20:21], 1.0 op_sel_hi:[1,0]
	v_pk_add_f32 v[50:51], v[30:31], 1.0 op_sel_hi:[1,0]
	v_pk_add_f32 v[48:49], v[28:29], 1.0 op_sel_hi:[1,0]
	s_and_b64 vcc, exec, s[0:1]
	s_cbranch_vccnz .Lap_h1_b
	v_mov_b64_e32 v[142:143], v[40:41]
	v_mov_b64_e32 v[144:145], v[42:43]
	v_mov_b64_e32 v[146:147], v[48:49]
	v_mov_b64_e32 v[148:149], v[50:51]
	v_mov_b64_e32 v[154:155], v[24:25]
	v_mov_b64_e32 v[156:157], v[26:27]
	v_mov_b64_e32 v[158:159], v[32:33]
	v_mov_b64_e32 v[160:161], v[34:35]
	v_pk_add_f32 v[166:167], v[166:167], 1.0 op_sel_hi:[1,0]
	v_pk_add_f32 v[168:169], v[168:169], 1.0 op_sel_hi:[1,0]
	v_pk_add_f32 v[170:171], v[170:171], 1.0 op_sel_hi:[1,0]
	v_pk_add_f32 v[172:173], v[172:173], 1.0 op_sel_hi:[1,0]
.Lap_h1_b:
	s_branch .LBB0_988
.LBB0_981:
	s_cbranch_execnz .LBB0_953
	s_branch .LBB0_954

.LBB0_988:
	ds_read_b64 v[2:3], v110 offset:8192
	s_and_b64 vcc, exec, s[4:5]
	v_add_u32_e32 v0, v111, v99
	s_waitcnt lgkmcnt(0)
	v_sub_f32_e32 v21, v239, v2
	v_sub_f32_e32 v20, v238, v2
	v_sub_f32_e32 v23, v241, v2
	v_sub_f32_e32 v22, v240, v2
	v_pk_mul_f32 v[22:23], v[2:3], v[22:23] op_sel:[1,0]
	v_pk_mul_f32 v[20:21], v[2:3], v[20:21] op_sel:[1,0]
	s_waitcnt vmcnt(0)
	v_pk_fma_f32 v[52:53], v[12:13], v[22:23], v[16:17]
	v_pk_fma_f32 v[54:55], v[14:15], v[20:21], v[18:19]
	v_sub_f32_e32 v21, v231, v2
	v_sub_f32_e32 v20, v230, v2
	v_sub_f32_e32 v23, v233, v2
	v_sub_f32_e32 v22, v232, v2
	v_pk_mul_f32 v[22:23], v[2:3], v[22:23] op_sel:[1,0]
	v_pk_mul_f32 v[2:3], v[2:3], v[20:21] op_sel:[1,0]
	v_pk_fma_f32 v[56:57], v[4:5], v[22:23], v[8:9]
	v_pk_fma_f32 v[58:59], v[6:7], v[2:3], v[10:11]
	s_cbranch_vccnz .LBB0_1032
	v_mov_b64_e32 v[20:21], v[24:25]
	v_mov_b64_e32 v[28:29], v[32:33]
	v_mov_b64_e32 v[36:37], v[40:41]
	v_mov_b64_e32 v[44:45], v[48:49]
	s_and_b64 vcc, exec, s[0:1]
	v_mov_b64_e32 v[22:23], v[26:27]
	v_mov_b64_e32 v[30:31], v[34:35]
	v_mov_b64_e32 v[38:39], v[42:43]
	v_mov_b64_e32 v[46:47], v[50:51]
	v_bfrev_b32_e32 v220, 0.5
	v_mov_b32_e32 v222, 0x2400
	s_cbranch_vccnz .LBB0_991
	v_add_u32_e32 v2, 0xffffe000, v249
	v_lshrrev_b32_e32 v2, 10, v2
	s_movk_i32 s2, 0x1800
	v_mad_u32_u24 v2, v2, s2, s2
	s_movk_i32 s2, 0x1fff
	v_cmp_lt_i32_e32 vcc, s2, v249
	v_mov_b32_e32 v3, v1
	s_nop 0
	v_cndmask_b32_e32 v2, 0, v2, vcc
	v_cmp_ne_u32_e32 vcc, s68, v2
	v_cndmask_b32_e32 v38, v144, v168, vcc
	v_cndmask_b32_e32 v39, v145, v169, vcc
	v_cndmask_b32_e32 v36, v142, v166, vcc
	v_cndmask_b32_e32 v37, v143, v167, vcc
	v_cndmask_b32_e32 v46, v148, v172, vcc
	v_cndmask_b32_e32 v47, v149, v173, vcc
	v_cndmask_b32_e32 v44, v146, v170, vcc
	v_cndmask_b32_e32 v45, v147, v171, vcc
	v_cndmask_b32_e32 v20, v154, v178, vcc
	v_cndmask_b32_e32 v21, v155, v179, vcc
	v_cndmask_b32_e32 v22, v156, v180, vcc
	v_cndmask_b32_e32 v23, v157, v181, vcc
	v_cndmask_b32_e32 v28, v158, v182, vcc
	v_cndmask_b32_e32 v29, v159, v183, vcc
	v_cndmask_b32_e32 v30, v160, v184, vcc
	v_cndmask_b32_e32 v31, v161, v185, vcc

.LBB0_993:
	ds_read_b64 v[2:3], v110 offset:8320
	s_and_b64 vcc, exec, s[4:5]
	v_add_u32_e32 v0, v112, v99
	s_waitcnt lgkmcnt(0)
	v_sub_f32_e32 v25, v97, v2
	v_sub_f32_e32 v24, v96, v2
	v_sub_f32_e32 v27, v191, v2
	v_sub_f32_e32 v26, v190, v2
	v_pk_mul_f32 v[26:27], v[2:3], v[26:27] op_sel:[1,0]
	v_pk_mul_f32 v[24:25], v[2:3], v[24:25] op_sel:[1,0]
	v_pk_fma_f32 v[52:53], v[12:13], v[26:27], v[16:17]
	v_pk_fma_f32 v[54:55], v[14:15], v[24:25], v[18:19]
	v_sub_f32_e32 v25, v93, v2
	v_sub_f32_e32 v24, v92, v2
	v_sub_f32_e32 v27, v95, v2
	v_sub_f32_e32 v26, v94, v2
	v_pk_mul_f32 v[26:27], v[2:3], v[26:27] op_sel:[1,0]
	v_pk_mul_f32 v[2:3], v[2:3], v[24:25] op_sel:[1,0]
	v_pk_fma_f32 v[56:57], v[4:5], v[26:27], v[8:9]
	v_pk_fma_f32 v[58:59], v[6:7], v[2:3], v[10:11]
	s_cbranch_vccnz .LBB0_1033
	v_mov_b64_e32 v[26:27], v[22:23]
	v_mov_b64_e32 v[34:35], v[30:31]
	v_mov_b64_e32 v[42:43], v[38:39]
	v_mov_b64_e32 v[50:51], v[46:47]
	s_and_b64 vcc, exec, s[0:1]
	v_mov_b64_e32 v[24:25], v[20:21]
	v_mov_b64_e32 v[32:33], v[28:29]
	v_mov_b64_e32 v[40:41], v[36:37]
	v_mov_b64_e32 v[48:49], v[44:45]
	s_cbranch_vccnz .LBB0_996
	v_add_u32_e32 v2, 0xffffe010, v249
	v_lshrrev_b32_e32 v2, 10, v2
	s_movk_i32 s2, 0x1800
	v_mad_u32_u24 v2, v2, s2, s2
	s_movk_i32 s2, 0x1fef
	v_cmp_lt_i32_e32 vcc, s2, v249
	v_mov_b32_e32 v3, v1
	s_nop 0
	v_cndmask_b32_e32 v2, 0, v2, vcc
	v_cmp_ne_u32_e32 vcc, s68, v2
	v_cndmask_b32_e32 v42, v144, v168, vcc
	v_cndmask_b32_e32 v43, v145, v169, vcc
	v_cndmask_b32_e32 v40, v142, v166, vcc
	v_cndmask_b32_e32 v41, v143, v167, vcc
	v_cndmask_b32_e32 v50, v148, v172, vcc
	v_cndmask_b32_e32 v51, v149, v173, vcc
	v_cndmask_b32_e32 v48, v146, v170, vcc
	v_cndmask_b32_e32 v49, v147, v171, vcc
	v_cndmask_b32_e32 v24, v154, v178, vcc
	v_cndmask_b32_e32 v25, v155, v179, vcc
	v_cndmask_b32_e32 v26, v156, v180, vcc
	v_cndmask_b32_e32 v27, v157, v181, vcc
	v_cndmask_b32_e32 v32, v158, v182, vcc
	v_cndmask_b32_e32 v33, v159, v183, vcc
	v_cndmask_b32_e32 v34, v160, v184, vcc
	v_cndmask_b32_e32 v35, v161, v185, vcc

.LBB0_998:
	ds_read_b64 v[2:3], v110 offset:8448
	s_and_b64 vcc, exec, s[4:5]
	v_add_u32_e32 v0, v113, v99
	s_waitcnt lgkmcnt(0)
	v_sub_f32_e32 v21, v89, v2
	v_sub_f32_e32 v20, v88, v2
	v_sub_f32_e32 v23, v91, v2
	v_sub_f32_e32 v22, v90, v2
	v_pk_mul_f32 v[22:23], v[2:3], v[22:23] op_sel:[1,0]
	v_pk_mul_f32 v[20:21], v[2:3], v[20:21] op_sel:[1,0]
	v_pk_fma_f32 v[52:53], v[12:13], v[22:23], v[16:17]
	v_pk_fma_f32 v[54:55], v[14:15], v[20:21], v[18:19]
	v_sub_f32_e32 v21, v85, v2
	v_sub_f32_e32 v20, v84, v2
	v_sub_f32_e32 v23, v87, v2
	v_sub_f32_e32 v22, v86, v2
	v_pk_mul_f32 v[22:23], v[2:3], v[22:23] op_sel:[1,0]
	v_pk_mul_f32 v[2:3], v[2:3], v[20:21] op_sel:[1,0]
	v_pk_fma_f32 v[56:57], v[4:5], v[22:23], v[8:9]
	v_pk_fma_f32 v[58:59], v[6:7], v[2:3], v[10:11]
	s_cbranch_vccnz .LBB0_1034
	v_mov_b64_e32 v[20:21], v[24:25]
	v_mov_b64_e32 v[28:29], v[32:33]
	v_mov_b64_e32 v[36:37], v[40:41]
	v_mov_b64_e32 v[44:45], v[48:49]
	s_and_b64 vcc, exec, s[0:1]
	v_mov_b64_e32 v[22:23], v[26:27]
	v_mov_b64_e32 v[30:31], v[34:35]
	v_mov_b64_e32 v[38:39], v[42:43]
	v_mov_b64_e32 v[46:47], v[50:51]
	s_cbranch_vccnz .LBB0_1001
	v_add_u32_e32 v2, 0xffffe020, v249
	v_lshrrev_b32_e32 v2, 10, v2
	s_movk_i32 s2, 0x1800
	v_mad_u32_u24 v2, v2, s2, s2
	s_movk_i32 s2, 0x1fdf
	v_cmp_lt_i32_e32 vcc, s2, v249
	v_mov_b32_e32 v3, v1
	s_nop 0
	v_cndmask_b32_e32 v2, 0, v2, vcc
	v_cmp_ne_u32_e32 vcc, s68, v2
	v_cndmask_b32_e32 v38, v144, v168, vcc
	v_cndmask_b32_e32 v39, v145, v169, vcc
	v_cndmask_b32_e32 v36, v142, v166, vcc
	v_cndmask_b32_e32 v37, v143, v167, vcc
	v_cndmask_b32_e32 v46, v148, v172, vcc
	v_cndmask_b32_e32 v47, v149, v173, vcc
	v_cndmask_b32_e32 v44, v146, v170, vcc
	v_cndmask_b32_e32 v45, v147, v171, vcc
	v_cndmask_b32_e32 v20, v154, v178, vcc
	v_cndmask_b32_e32 v21, v155, v179, vcc
	v_cndmask_b32_e32 v22, v156, v180, vcc
	v_cndmask_b32_e32 v23, v157, v181, vcc
	v_cndmask_b32_e32 v28, v158, v182, vcc
	v_cndmask_b32_e32 v29, v159, v183, vcc
	v_cndmask_b32_e32 v30, v160, v184, vcc
	v_cndmask_b32_e32 v31, v161, v185, vcc

.LBB0_1003:
	ds_read_b64 v[2:3], v110 offset:8960
	s_and_b64 vcc, exec, s[4:5]
	v_add_u32_e32 v0, v118, v99
	s_waitcnt lgkmcnt(0)
	v_sub_f32_e32 v25, v81, v2
	v_sub_f32_e32 v24, v80, v2
	v_sub_f32_e32 v27, v83, v2
	v_sub_f32_e32 v26, v82, v2
	v_pk_mul_f32 v[26:27], v[2:3], v[26:27] op_sel:[1,0]
	v_pk_mul_f32 v[24:25], v[2:3], v[24:25] op_sel:[1,0]
	v_pk_fma_f32 v[52:53], v[12:13], v[26:27], v[16:17]
	v_pk_fma_f32 v[54:55], v[14:15], v[24:25], v[18:19]
	v_sub_f32_e32 v25, v77, v2
	v_sub_f32_e32 v24, v76, v2
	v_sub_f32_e32 v27, v79, v2
	v_sub_f32_e32 v26, v78, v2
	v_pk_mul_f32 v[26:27], v[2:3], v[26:27] op_sel:[1,0]
	v_pk_mul_f32 v[2:3], v[2:3], v[24:25] op_sel:[1,0]
	v_pk_fma_f32 v[56:57], v[4:5], v[26:27], v[8:9]
	v_pk_fma_f32 v[58:59], v[6:7], v[2:3], v[10:11]
	s_cbranch_vccnz .LBB0_1035
	v_mov_b64_e32 v[26:27], v[22:23]
	v_mov_b64_e32 v[34:35], v[30:31]
	v_mov_b64_e32 v[42:43], v[38:39]
	v_mov_b64_e32 v[50:51], v[46:47]
	s_and_b64 vcc, exec, s[0:1]
	v_mov_b64_e32 v[24:25], v[20:21]
	v_mov_b64_e32 v[32:33], v[28:29]
	v_mov_b64_e32 v[40:41], v[36:37]
	v_mov_b64_e32 v[48:49], v[44:45]
	s_cbranch_vccnz .LBB0_1006
	v_add_u32_e32 v2, 0xffffe060, v249
	v_lshrrev_b32_e32 v2, 10, v2
	s_movk_i32 s2, 0x1800
	v_mad_u32_u24 v2, v2, s2, s2
	s_movk_i32 s2, 0x1f9f
	v_cmp_lt_i32_e32 vcc, s2, v249
	v_mov_b32_e32 v3, v1
	s_nop 0
	v_cndmask_b32_e32 v2, 0, v2, vcc
	v_cmp_ne_u32_e32 vcc, s68, v2
	v_cndmask_b32_e32 v42, v144, v168, vcc
	v_cndmask_b32_e32 v43, v145, v169, vcc
	v_cndmask_b32_e32 v40, v142, v166, vcc
	v_cndmask_b32_e32 v41, v143, v167, vcc
	v_cndmask_b32_e32 v50, v148, v172, vcc
	v_cndmask_b32_e32 v51, v149, v173, vcc
	v_cndmask_b32_e32 v48, v146, v170, vcc
	v_cndmask_b32_e32 v49, v147, v171, vcc
	v_cndmask_b32_e32 v24, v154, v178, vcc
	v_cndmask_b32_e32 v25, v155, v179, vcc
	v_cndmask_b32_e32 v26, v156, v180, vcc
	v_cndmask_b32_e32 v27, v157, v181, vcc
	v_cndmask_b32_e32 v32, v158, v182, vcc
	v_cndmask_b32_e32 v33, v159, v183, vcc
	v_cndmask_b32_e32 v34, v160, v184, vcc
	v_cndmask_b32_e32 v35, v161, v185, vcc

.LBB0_1008:
	ds_read_b64 v[2:3], v110 offset:9088
	s_and_b64 vcc, exec, s[4:5]
	v_add_u32_e32 v0, v114, v99
	s_waitcnt lgkmcnt(0)
	v_sub_f32_e32 v21, v73, v2
	v_sub_f32_e32 v20, v72, v2
	v_sub_f32_e32 v23, v75, v2
	v_sub_f32_e32 v22, v74, v2
	v_pk_mul_f32 v[22:23], v[2:3], v[22:23] op_sel:[1,0]
	v_pk_mul_f32 v[20:21], v[2:3], v[20:21] op_sel:[1,0]
	v_pk_fma_f32 v[52:53], v[12:13], v[22:23], v[16:17]
	v_pk_fma_f32 v[54:55], v[14:15], v[20:21], v[18:19]
	v_sub_f32_e32 v21, v69, v2
	v_sub_f32_e32 v20, v68, v2
	v_sub_f32_e32 v23, v71, v2
	v_sub_f32_e32 v22, v70, v2
	v_pk_mul_f32 v[22:23], v[2:3], v[22:23] op_sel:[1,0]
	v_pk_mul_f32 v[2:3], v[2:3], v[20:21] op_sel:[1,0]
	v_pk_fma_f32 v[56:57], v[4:5], v[22:23], v[8:9]
	v_pk_fma_f32 v[58:59], v[6:7], v[2:3], v[10:11]
	s_cbranch_vccnz .LBB0_1036
	v_mov_b64_e32 v[30:31], v[26:27]
	v_mov_b64_e32 v[20:21], v[32:33]
	v_mov_b64_e32 v[36:37], v[40:41]
	v_mov_b64_e32 v[44:45], v[48:49]
	s_and_b64 vcc, exec, s[0:1]
	v_mov_b64_e32 v[28:29], v[24:25]
	v_mov_b64_e32 v[22:23], v[34:35]
	v_mov_b64_e32 v[38:39], v[42:43]
	v_mov_b64_e32 v[46:47], v[50:51]
	s_cbranch_vccnz .LBB0_1011
	v_add_u32_e32 v2, 0xffffe070, v249
	v_lshrrev_b32_e32 v2, 10, v2
	s_movk_i32 s2, 0x1800
	v_mad_u32_u24 v2, v2, s2, s2
	s_movk_i32 s2, 0x1f8f
	v_cmp_lt_i32_e32 vcc, s2, v249
	v_mov_b32_e32 v3, v1
	s_nop 0
	v_cndmask_b32_e32 v2, 0, v2, vcc
	v_cmp_ne_u32_e32 vcc, s68, v2
	v_cndmask_b32_e32 v38, v144, v168, vcc
	v_cndmask_b32_e32 v39, v145, v169, vcc
	v_cndmask_b32_e32 v36, v142, v166, vcc
	v_cndmask_b32_e32 v37, v143, v167, vcc
	v_cndmask_b32_e32 v46, v148, v172, vcc
	v_cndmask_b32_e32 v47, v149, v173, vcc
	v_cndmask_b32_e32 v44, v146, v170, vcc
	v_cndmask_b32_e32 v45, v147, v171, vcc
	v_cndmask_b32_e32 v28, v154, v178, vcc
	v_cndmask_b32_e32 v29, v155, v179, vcc
	v_cndmask_b32_e32 v30, v156, v180, vcc
	v_cndmask_b32_e32 v31, v157, v181, vcc
	v_cndmask_b32_e32 v20, v158, v182, vcc
	v_cndmask_b32_e32 v21, v159, v183, vcc
	v_cndmask_b32_e32 v22, v160, v184, vcc
	v_cndmask_b32_e32 v23, v161, v185, vcc

.LBB0_1013:
	ds_read_b64 v[2:3], v110 offset:9216
	s_and_b64 vcc, exec, s[4:5]
	v_add_u32_e32 v0, v98, v99
	s_waitcnt lgkmcnt(0)
	v_sub_f32_e32 v25, v65, v2
	v_sub_f32_e32 v24, v64, v2
	v_sub_f32_e32 v27, v67, v2
	v_sub_f32_e32 v26, v66, v2
	v_pk_mul_f32 v[26:27], v[2:3], v[26:27] op_sel:[1,0]
	v_pk_mul_f32 v[24:25], v[2:3], v[24:25] op_sel:[1,0]
	v_pk_fma_f32 v[12:13], v[12:13], v[26:27], v[16:17]
	v_pk_fma_f32 v[14:15], v[14:15], v[24:25], v[18:19]
	v_sub_f32_e32 v17, v61, v2
	v_sub_f32_e32 v16, v60, v2
	v_sub_f32_e32 v19, v63, v2
	v_sub_f32_e32 v18, v62, v2
	v_pk_mul_f32 v[18:19], v[2:3], v[18:19] op_sel:[1,0]
	v_pk_mul_f32 v[2:3], v[2:3], v[16:17] op_sel:[1,0]
	v_pk_fma_f32 v[4:5], v[4:5], v[18:19], v[8:9]
	v_pk_fma_f32 v[6:7], v[6:7], v[2:3], v[10:11]
	s_cbranch_vccnz .LBB0_1037
	s_and_b64 vcc, exec, s[0:1]
	s_cbranch_vccnz .LBB0_1016
	v_add_u32_e32 v2, 0xffffe080, v249
	v_lshrrev_b32_e32 v2, 10, v2
	s_movk_i32 s0, 0x1800
	v_mad_u32_u24 v2, v2, s0, s0
	s_movk_i32 s0, 0x1f7f
	v_cmp_lt_i32_e32 vcc, s0, v249
	v_mov_b32_e32 v3, v1
	s_nop 0
	v_cndmask_b32_e32 v2, 0, v2, vcc
	v_cmp_ne_u32_e32 vcc, s68, v2
	v_cndmask_b32_e32 v38, v144, v168, vcc
	v_cndmask_b32_e32 v39, v145, v169, vcc
	v_cndmask_b32_e32 v36, v142, v166, vcc
	v_cndmask_b32_e32 v37, v143, v167, vcc
	v_cndmask_b32_e32 v46, v148, v172, vcc
	v_cndmask_b32_e32 v47, v149, v173, vcc
	v_cndmask_b32_e32 v44, v146, v170, vcc
	v_cndmask_b32_e32 v45, v147, v171, vcc
	v_cndmask_b32_e32 v28, v154, v178, vcc
	v_cndmask_b32_e32 v29, v155, v179, vcc
	v_cndmask_b32_e32 v30, v156, v180, vcc
	v_cndmask_b32_e32 v31, v157, v181, vcc
	v_cndmask_b32_e32 v20, v158, v182, vcc
	v_cndmask_b32_e32 v21, v159, v183, vcc
	v_cndmask_b32_e32 v22, v160, v184, vcc
	v_cndmask_b32_e32 v23, v161, v185, vcc
